# trailing-half priority raise kept through the ConvGLU epilogue of the up-projection GEMM (reset at the phase exit), on top of v44
# baseline (speedup 1.0000x reference)
; #define PG8_STAGE(bufoff, gbase, voff) do { _Pragma("unroll") for (int _i = 0; _i < 2; ++_i) \
;         __builtin_amdgcn_global_load_lds((const unsigned*)((const char*)(gbase) + (voff)[_i]), (PG8_LAS unsigned*)(lds + (bufoff) + ldsw + _i * 8192), 16, 0, 0); } while (0)
; #define PG8_LDA(dst, b, h) do { _Pragma("unroll") for (int m = 0; m < 4; ++m) _Pragma("unroll") for (int k = 0; k < 2; ++k) dst[m][k] = *(const PG8_LAS bf16x8*)(lds + PG8_SA(b, h) + aoff + m * 2048 + k * 1024); } while (0)
; #define PG8_LDB(dst, b, h) do { _Pragma("unroll") for (int n = 0; n < 2; ++n) _Pragma("unroll") for (int k = 0; k < 2; ++k) dst[n][k] = *(const PG8_LAS bf16x8*)(lds + PG8_SB(b, h) + boff + n * 2048 + k * 1024); } while (0)
; #define PG8_MMA(ai, bj, At, Bt) do { __builtin_amdgcn_s_setprio(1); _Pragma("unroll") for (int m = 0; m < 4; ++m) _Pragma("unroll") for (int n = 0; n < 2; ++n) _Pragma("unroll") for (int k = 0; k < 2; ++k) \
;         acc[ai][bj][m][n] = __builtin_amdgcn_mfma_f32_16x16x32_bf16(Bt[n][k], At[m][k], acc[ai][bj][m][n], 0, 0, 0); __builtin_amdgcn_s_setprio(0); } while (0)
; #define PG8_WAIT_V(n) asm volatile("s_waitcnt vmcnt(" #n ")" ::: "memory")
; #define PG8_WAIT_L(n) asm volatile("s_waitcnt lgkmcnt(" #n ")" ::: "memory")
; #define PG8_BAR __builtin_amdgcn_s_barrier()
; #define PG8_SCHED __builtin_amdgcn_sched_barrier(0)
; template <class Epi, class Sched, bool ALIGN_EPI = false, bool SP2 = false>
; __device__ __forceinline__ void gemm_phase(PG8_LAS unsigned char* lds, const Gemm g, const Sched& S, const Epi& E) {
;     ...
;             PG8_LDB(B0, 0, 0); PG8_LDB(B1, 0, 1); PG8_SCHED; PG8_LDA(At, 0, 0); PG8_STAGE(PG8_SA(1, 1), a1 + hstep, voffA);
;             PG8_WAIT_V(8); PG8_WAIT_L(0); PG8_BAR; PG8_MMA(0, 0, At, B0); PG8_MMA(0, 1, At, B1); PG8_BAR; PG8_SCHED;
;             PG8_LDA(At, 0, 1); PG8_STAGE(PG8_SB(0, 0), b2, voffB); PG8_STAGE(PG8_SB(0, 1), b2 + hstep, voffB); PG8_STAGE(PG8_SA(0, 0), a2, voffA);
.LBB0_882:
	ds_read_b128 v[128:131], v187
	ds_read_b128 v[132:135], v188
	ds_read_b128 v[136:139], v187 offset:2048
	ds_read_b128 v[140:143], v188 offset:2048
	ds_read_b128 v[168:171], v187 offset:16384
	ds_read_b128 v[172:175], v188 offset:16384
	ds_read_b128 v[176:179], v187 offset:18432
	ds_read_b128 v[194:197], v188 offset:18432
	s_add_u32 s20, s18, 0xfff80080
	s_addc_u32 s21, s19, -1
	s_cmp_eq_u32 s78, 28
	s_cselect_b32 s55, s15, s21
	s_cselect_b32 s54, s17, s20
	s_cselect_b32 s21, s47, s77
	s_cselect_b32 s20, s49, s76
	v_lshl_add_u64 v[180:181], s[18:19], 0, v[160:161]
	s_add_i32 m0, s60, 0xc000
	ds_read_b128 v[198:201], v189
	ds_read_b128 v[202:205], v242
	ds_read_b128 v[206:209], v189 offset:2048
	ds_read_b128 v[210:213], v242 offset:2048
	ds_read_b128 v[214:217], v189 offset:4096
	ds_read_b128 v[218:221], v242 offset:4096
	ds_read_b128 v[222:225], v189 offset:6144
	ds_read_b128 v[226:229], v242 offset:6144
	global_load_lds_dwordx4 v[180:181], off
	v_lshl_add_u64 v[180:181], s[18:19], 0, v[162:163]
	s_add_i32 m0, s60, 0xe000
	s_nop 0
	global_load_lds_dwordx4 v[180:181], off
	s_waitcnt vmcnt(8)
	s_waitcnt lgkmcnt(0)
	s_barrier
	s_waitcnt lgkmcnt(0)
	v_mfma_f32_16x16x32_bf16 v[120:123], v[128:131], v[198:201], v[120:123]
	v_mfma_f32_16x16x32_bf16 v[88:91], v[136:139], v[198:201], v[88:91]
	v_mfma_f32_16x16x32_bf16 v[116:119], v[128:131], v[206:209], v[116:119]
	v_mfma_f32_16x16x32_bf16 v[84:87], v[136:139], v[206:209], v[84:87]
	v_mfma_f32_16x16x32_bf16 v[112:115], v[128:131], v[214:217], v[112:115]
	v_mfma_f32_16x16x32_bf16 v[80:83], v[136:139], v[214:217], v[80:83]
	v_mfma_f32_16x16x32_bf16 v[100:103], v[128:131], v[222:225], v[100:103]
	v_mfma_f32_16x16x32_bf16 v[68:71], v[136:139], v[222:225], v[68:71]
	v_mfma_f32_16x16x32_bf16 v[120:123], v[132:135], v[202:205], v[120:123]
	v_mfma_f32_16x16x32_bf16 v[88:91], v[140:143], v[202:205], v[88:91]
	v_mfma_f32_16x16x32_bf16 v[116:119], v[132:135], v[210:213], v[116:119]
	v_mfma_f32_16x16x32_bf16 v[84:87], v[140:143], v[210:213], v[84:87]
	v_mfma_f32_16x16x32_bf16 v[112:115], v[132:135], v[218:221], v[112:115]
	v_mfma_f32_16x16x32_bf16 v[80:83], v[140:143], v[218:221], v[80:83]
	v_mfma_f32_16x16x32_bf16 v[100:103], v[132:135], v[226:229], v[100:103]
	v_mfma_f32_16x16x32_bf16 v[68:71], v[140:143], v[226:229], v[68:71]
	v_mfma_f32_16x16x32_bf16 v[124:127], v[168:171], v[198:201], v[124:127]
	v_mfma_f32_16x16x32_bf16 v[92:95], v[176:179], v[198:201], v[92:95]
	v_mfma_f32_16x16x32_bf16 v[108:111], v[168:171], v[206:209], v[108:111]
	v_mfma_f32_16x16x32_bf16 v[76:79], v[176:179], v[206:209], v[76:79]
	v_mfma_f32_16x16x32_bf16 v[104:107], v[168:171], v[214:217], v[104:107]
	v_mfma_f32_16x16x32_bf16 v[72:75], v[176:179], v[214:217], v[72:75]
	v_mfma_f32_16x16x32_bf16 v[96:99], v[168:171], v[222:225], v[96:99]
	v_mfma_f32_16x16x32_bf16 v[64:67], v[176:179], v[222:225], v[64:67]
	v_mfma_f32_16x16x32_bf16 v[124:127], v[172:175], v[202:205], v[124:127]
	v_mfma_f32_16x16x32_bf16 v[92:95], v[194:197], v[202:205], v[92:95]
	v_mfma_f32_16x16x32_bf16 v[108:111], v[172:175], v[210:213], v[108:111]
	v_mfma_f32_16x16x32_bf16 v[76:79], v[194:197], v[210:213], v[76:79]
	v_mfma_f32_16x16x32_bf16 v[104:107], v[172:175], v[218:221], v[104:107]
	v_mfma_f32_16x16x32_bf16 v[72:75], v[194:197], v[218:221], v[72:75]
	v_mfma_f32_16x16x32_bf16 v[96:99], v[172:175], v[226:229], v[96:99]
	v_mfma_f32_16x16x32_bf16 v[64:67], v[194:197], v[226:229], v[64:67]
	s_barrier
	s_add_i32 s36, s72, s59
	v_lshl_add_u64 v[180:181], s[20:21], 0, v[148:149]
	s_mov_b32 m0, s36
	ds_read_b128 v[198:201], v189 offset:16384
	ds_read_b128 v[202:205], v242 offset:16384
	ds_read_b128 v[206:209], v189 offset:18432
	ds_read_b128 v[210:213], v242 offset:18432
	ds_read_b128 v[214:217], v189 offset:20480
	ds_read_b128 v[218:221], v242 offset:20480
	ds_read_b128 v[222:225], v189 offset:22528
	ds_read_b128 v[226:229], v242 offset:22528
	global_load_lds_dwordx4 v[180:181], off
	s_add_i32 m0, s36, 0x2000
	s_add_u32 s36, s20, 0x80000
	v_lshl_add_u64 v[230:231], s[20:21], 0, v[152:153]
	s_addc_u32 s37, s21, 0
	s_add_i32 s79, s73, s59
	global_load_lds_dwordx4 v[230:231], off
	v_lshl_add_u64 v[232:233], s[36:37], 0, v[148:149]
	s_mov_b32 m0, s79
	v_lshl_add_u64 v[234:235], s[54:55], 0, v[150:151]
	global_load_lds_dwordx4 v[232:233], off
	v_lshl_add_u64 v[232:233], s[36:37], 0, v[152:153]
	s_add_i32 m0, s79, 0x2000
	s_nop 0
	global_load_lds_dwordx4 v[232:233], off
	v_lshl_add_u64 v[232:233], s[54:55], 0, v[146:147]
	s_mov_b32 m0, s60
	s_nop 0
	global_load_lds_dwordx4 v[232:233], off
	s_mov_b32 m0, s61
	s_nop 0
	global_load_lds_dwordx4 v[234:235], off
	s_waitcnt vmcnt(8)
	s_waitcnt lgkmcnt(0)
	s_barrier
; #define PG8_STAGE(bufoff, gbase, voff) do { _Pragma("unroll") for (int _i = 0; _i < 2; ++_i) \
;         __builtin_amdgcn_global_load_lds((const unsigned*)((const char*)(gbase) + (voff)[_i]), (PG8_LAS unsigned*)(lds + (bufoff) + ldsw + _i * 8192), 16, 0, 0); } while (0)
; #define PG8_LDA(dst, b, h) do { _Pragma("unroll") for (int m = 0; m < 4; ++m) _Pragma("unroll") for (int k = 0; k < 2; ++k) dst[m][k] = *(const PG8_LAS bf16x8*)(lds + PG8_SA(b, h) + aoff + m * 2048 + k * 1024); } while (0)
; #define PG8_LDB(dst, b, h) do { _Pragma("unroll") for (int n = 0; n < 2; ++n) _Pragma("unroll") for (int k = 0; k < 2; ++k) dst[n][k] = *(const PG8_LAS bf16x8*)(lds + PG8_SB(b, h) + boff + n * 2048 + k * 1024); } while (0)
; #define PG8_MMA(ai, bj, At, Bt) do { __builtin_amdgcn_s_setprio(1); _Pragma("unroll") for (int m = 0; m < 4; ++m) _Pragma("unroll") for (int n = 0; n < 2; ++n) _Pragma("unroll") for (int k = 0; k < 2; ++k) \
;         acc[ai][bj][m][n] = __builtin_amdgcn_mfma_f32_16x16x32_bf16(Bt[n][k], At[m][k], acc[ai][bj][m][n], 0, 0, 0); __builtin_amdgcn_s_setprio(0); } while (0)
; #define PG8_WAIT_V(n) asm volatile("s_waitcnt vmcnt(" #n ")" ::: "memory")
; #define PG8_WAIT_L(n) asm volatile("s_waitcnt lgkmcnt(" #n ")" ::: "memory")
; #define PG8_BAR __builtin_amdgcn_s_barrier()
; #define PG8_SCHED __builtin_amdgcn_sched_barrier(0)
; template <class Epi, class Sched, bool ALIGN_EPI = false, bool SP2 = false>
; __device__ __forceinline__ void gemm_phase(PG8_LAS unsigned char* lds, const Gemm g, const Sched& S, const Epi& E) {
;     ...
;             PG8_WAIT_V(8); PG8_WAIT_L(0); PG8_BAR; PG8_MMA(1, 0, At, B0); PG8_MMA(1, 1, At, B1); PG8_BAR; PG8_SCHED;
;             PG8_LDB(B0, 1, 0); PG8_LDB(B1, 1, 1); PG8_SCHED; PG8_LDA(At, 1, 0); PG8_STAGE(PG8_SA(0, 1), a2 + hstep, voffA);
;             PG8_WAIT_V(8); PG8_WAIT_L(0); PG8_BAR; PG8_MMA(0, 0, At, B0); PG8_MMA(0, 1, At, B1); PG8_BAR; PG8_SCHED;
	s_waitcnt lgkmcnt(0)
	v_mfma_f32_16x16x32_bf16 v[60:63], v[128:131], v[198:201], v[60:63]
	v_mfma_f32_16x16x32_bf16 v[28:31], v[136:139], v[198:201], v[28:31]
	v_mfma_f32_16x16x32_bf16 v[52:55], v[128:131], v[206:209], v[52:55]
	v_mfma_f32_16x16x32_bf16 v[20:23], v[136:139], v[206:209], v[20:23]
	v_mfma_f32_16x16x32_bf16 v[48:51], v[128:131], v[214:217], v[48:51]
	v_mfma_f32_16x16x32_bf16 v[16:19], v[136:139], v[214:217], v[16:19]
	v_mfma_f32_16x16x32_bf16 v[44:47], v[128:131], v[222:225], v[44:47]
	v_mfma_f32_16x16x32_bf16 v[8:11], v[136:139], v[222:225], v[8:11]
	v_mfma_f32_16x16x32_bf16 v[60:63], v[132:135], v[202:205], v[60:63]
	v_mfma_f32_16x16x32_bf16 v[28:31], v[140:143], v[202:205], v[28:31]
	v_mfma_f32_16x16x32_bf16 v[52:55], v[132:135], v[210:213], v[52:55]
	v_mfma_f32_16x16x32_bf16 v[20:23], v[140:143], v[210:213], v[20:23]
	v_mfma_f32_16x16x32_bf16 v[48:51], v[132:135], v[218:221], v[48:51]
	v_mfma_f32_16x16x32_bf16 v[16:19], v[140:143], v[218:221], v[16:19]
	v_mfma_f32_16x16x32_bf16 v[44:47], v[132:135], v[226:229], v[44:47]
	v_mfma_f32_16x16x32_bf16 v[8:11], v[140:143], v[226:229], v[8:11]
	v_mfma_f32_16x16x32_bf16 v[56:59], v[168:171], v[198:201], v[56:59]
	v_mfma_f32_16x16x32_bf16 v[24:27], v[176:179], v[198:201], v[24:27]
	v_mfma_f32_16x16x32_bf16 v[40:43], v[168:171], v[206:209], v[40:43]
	v_mfma_f32_16x16x32_bf16 v[12:15], v[176:179], v[206:209], v[12:15]
	v_mfma_f32_16x16x32_bf16 v[36:39], v[168:171], v[214:217], v[36:39]
	v_mfma_f32_16x16x32_bf16 v[4:7], v[176:179], v[214:217], v[4:7]
	v_mfma_f32_16x16x32_bf16 v[32:35], v[168:171], v[222:225], v[32:35]
	v_mfma_f32_16x16x32_bf16 v[0:3], v[176:179], v[222:225], v[0:3]
	v_mfma_f32_16x16x32_bf16 v[56:59], v[172:175], v[202:205], v[56:59]
	v_mfma_f32_16x16x32_bf16 v[24:27], v[194:197], v[202:205], v[24:27]
	v_mfma_f32_16x16x32_bf16 v[40:43], v[172:175], v[210:213], v[40:43]
	v_mfma_f32_16x16x32_bf16 v[12:15], v[194:197], v[210:213], v[12:15]
	v_mfma_f32_16x16x32_bf16 v[36:39], v[172:175], v[218:221], v[36:39]
	v_mfma_f32_16x16x32_bf16 v[4:7], v[194:197], v[218:221], v[4:7]
	v_mfma_f32_16x16x32_bf16 v[32:35], v[172:175], v[226:229], v[32:35]
	v_mfma_f32_16x16x32_bf16 v[0:3], v[194:197], v[226:229], v[0:3]
	s_barrier
	s_add_i32 s79, 0, 0x18000
	s_add_i32 s80, 0, 0x1c000
	v_add_u32_e32 v140, s79, v182
	v_add_u32_e32 v154, s80, v182
	ds_read_b128 v[128:131], v187 offset:32768
	ds_read_b128 v[132:135], v188 offset:32768
	ds_read_b128 v[136:139], v187 offset:34816
	ds_read_b128 v[140:143], v188 offset:34816
	ds_read_b128 v[168:171], v187 offset:49152
	ds_read_b128 v[172:175], v188 offset:49152
	ds_read_b128 v[176:179], v187 offset:51200
	ds_read_b128 v[194:197], v188 offset:51200
	s_add_u32 s36, s54, 0x80000
	s_addc_u32 s37, s55, 0
	s_mov_b32 m0, s62
	v_lshl_add_u64 v[236:237], s[36:37], 0, v[146:147]
	ds_read_b128 v[198:201], v189 offset:32768
	ds_read_b128 v[202:205], v242 offset:32768
	ds_read_b128 v[206:209], v189 offset:34816
	ds_read_b128 v[210:213], v242 offset:34816
	ds_read_b128 v[214:217], v189 offset:36864
	ds_read_b128 v[218:221], v242 offset:36864
	ds_read_b128 v[222:225], v189 offset:38912
	ds_read_b128 v[226:229], v242 offset:38912
	global_load_lds_dwordx4 v[236:237], off
	v_lshl_add_u64 v[236:237], s[36:37], 0, v[150:151]
	s_mov_b32 m0, s63
	s_nop 0
	global_load_lds_dwordx4 v[236:237], off
	s_waitcnt vmcnt(8)
	s_waitcnt lgkmcnt(0)
	s_barrier
	s_waitcnt lgkmcnt(0)
	v_mfma_f32_16x16x32_bf16 v[120:123], v[128:131], v[198:201], v[120:123]
	v_mfma_f32_16x16x32_bf16 v[88:91], v[136:139], v[198:201], v[88:91]
	v_mfma_f32_16x16x32_bf16 v[116:119], v[128:131], v[206:209], v[116:119]
	v_mfma_f32_16x16x32_bf16 v[84:87], v[136:139], v[206:209], v[84:87]
	v_mfma_f32_16x16x32_bf16 v[112:115], v[128:131], v[214:217], v[112:115]
	v_mfma_f32_16x16x32_bf16 v[80:83], v[136:139], v[214:217], v[80:83]
	v_mfma_f32_16x16x32_bf16 v[100:103], v[128:131], v[222:225], v[100:103]
	v_mfma_f32_16x16x32_bf16 v[68:71], v[136:139], v[222:225], v[68:71]
	v_mfma_f32_16x16x32_bf16 v[120:123], v[132:135], v[202:205], v[120:123]
	v_mfma_f32_16x16x32_bf16 v[88:91], v[140:143], v[202:205], v[88:91]
	v_mfma_f32_16x16x32_bf16 v[116:119], v[132:135], v[210:213], v[116:119]
	v_mfma_f32_16x16x32_bf16 v[84:87], v[140:143], v[210:213], v[84:87]
	v_mfma_f32_16x16x32_bf16 v[112:115], v[132:135], v[218:221], v[112:115]
	v_mfma_f32_16x16x32_bf16 v[80:83], v[140:143], v[218:221], v[80:83]
	v_mfma_f32_16x16x32_bf16 v[100:103], v[132:135], v[226:229], v[100:103]
	v_mfma_f32_16x16x32_bf16 v[68:71], v[140:143], v[226:229], v[68:71]
	v_mfma_f32_16x16x32_bf16 v[124:127], v[168:171], v[198:201], v[124:127]
	v_mfma_f32_16x16x32_bf16 v[92:95], v[176:179], v[198:201], v[92:95]
	v_mfma_f32_16x16x32_bf16 v[108:111], v[168:171], v[206:209], v[108:111]
	v_mfma_f32_16x16x32_bf16 v[76:79], v[176:179], v[206:209], v[76:79]
	v_mfma_f32_16x16x32_bf16 v[104:107], v[168:171], v[214:217], v[104:107]
	v_mfma_f32_16x16x32_bf16 v[72:75], v[176:179], v[214:217], v[72:75]
	v_mfma_f32_16x16x32_bf16 v[96:99], v[168:171], v[222:225], v[96:99]
	v_mfma_f32_16x16x32_bf16 v[64:67], v[176:179], v[222:225], v[64:67]
	v_mfma_f32_16x16x32_bf16 v[124:127], v[172:175], v[202:205], v[124:127]
	v_mfma_f32_16x16x32_bf16 v[92:95], v[194:197], v[202:205], v[92:95]
	v_mfma_f32_16x16x32_bf16 v[108:111], v[172:175], v[210:213], v[108:111]
	v_mfma_f32_16x16x32_bf16 v[76:79], v[194:197], v[210:213], v[76:79]
	v_mfma_f32_16x16x32_bf16 v[104:107], v[172:175], v[218:221], v[104:107]
	v_mfma_f32_16x16x32_bf16 v[72:75], v[194:197], v[218:221], v[72:75]
	v_mfma_f32_16x16x32_bf16 v[96:99], v[172:175], v[226:229], v[96:99]
	v_mfma_f32_16x16x32_bf16 v[64:67], v[194:197], v[226:229], v[64:67]
	s_barrier
; #define PG8_STAGE(bufoff, gbase, voff) do { _Pragma("unroll") for (int _i = 0; _i < 2; ++_i) \
;         __builtin_amdgcn_global_load_lds((const unsigned*)((const char*)(gbase) + (voff)[_i]), (PG8_LAS unsigned*)(lds + (bufoff) + ldsw + _i * 8192), 16, 0, 0); } while (0)
; #define PG8_LDA(dst, b, h) do { _Pragma("unroll") for (int m = 0; m < 4; ++m) _Pragma("unroll") for (int k = 0; k < 2; ++k) dst[m][k] = *(const PG8_LAS bf16x8*)(lds + PG8_SA(b, h) + aoff + m * 2048 + k * 1024); } while (0)
; #define PG8_MMA(ai, bj, At, Bt) do { __builtin_amdgcn_s_setprio(1); _Pragma("unroll") for (int m = 0; m < 4; ++m) _Pragma("unroll") for (int n = 0; n < 2; ++n) _Pragma("unroll") for (int k = 0; k < 2; ++k) \
;         acc[ai][bj][m][n] = __builtin_amdgcn_mfma_f32_16x16x32_bf16(Bt[n][k], At[m][k], acc[ai][bj][m][n], 0, 0, 0); __builtin_amdgcn_s_setprio(0); } while (0)
; #define PG8_WAIT_V(n) asm volatile("s_waitcnt vmcnt(" #n ")" ::: "memory")
; #define PG8_WAIT_L(n) asm volatile("s_waitcnt lgkmcnt(" #n ")" ::: "memory")
; #define PG8_BAR __builtin_amdgcn_s_barrier()
; #define PG8_SCHED __builtin_amdgcn_sched_barrier(0)
; template <class Epi, class Sched, bool ALIGN_EPI = false, bool SP2 = false>
; __device__ __forceinline__ void gemm_phase(PG8_LAS unsigned char* lds, const Gemm g, const Sched& S, const Epi& E) {
;     ...
;         for (int t = 0; t < nt; t += 2) {
;             const bool last = (t == nt - 2);
;     ...
;             PG8_LDA(At, 1, 1); PG8_STAGE(PG8_SB(1, 0), b3, voffB); PG8_STAGE(PG8_SB(1, 1), b3 + hstep, voffB); PG8_STAGE(PG8_SA(1, 0), a3, voffA);
;             PG8_WAIT_V(8); PG8_WAIT_L(0); PG8_BAR; PG8_MMA(1, 0, At, B0); PG8_MMA(1, 1, At, B1); PG8_BAR; PG8_SCHED;
	s_add_i32 s36, s79, s59
	v_lshl_add_u64 v[180:181], v[180:181], 0, s[28:29]
	s_mov_b32 m0, s36
	ds_read_b128 v[198:201], v189 offset:49152
	ds_read_b128 v[202:205], v242 offset:49152
	ds_read_b128 v[206:209], v189 offset:51200
	ds_read_b128 v[210:213], v242 offset:51200
	ds_read_b128 v[214:217], v189 offset:53248
	ds_read_b128 v[218:221], v242 offset:53248
	ds_read_b128 v[222:225], v189 offset:55296
	ds_read_b128 v[226:229], v242 offset:55296
	global_load_lds_dwordx4 v[180:181], off
	s_add_i32 m0, s36, 0x2000
	s_add_u32 s20, s20, 0x80080
	v_lshl_add_u64 v[180:181], v[230:231], 0, s[28:29]
	s_addc_u32 s21, s21, 0
	s_add_i32 s36, s80, s59
	global_load_lds_dwordx4 v[180:181], off
	v_lshl_add_u64 v[180:181], s[20:21], 0, v[148:149]
	s_mov_b32 m0, s36
	s_nop 0
	global_load_lds_dwordx4 v[180:181], off
	v_lshl_add_u64 v[180:181], s[20:21], 0, v[152:153]
	s_add_i32 m0, s36, 0x2000
	s_nop 0
	global_load_lds_dwordx4 v[180:181], off
	v_lshl_add_u64 v[180:181], v[232:233], 0, s[28:29]
	s_mov_b32 m0, s67
	s_nop 0
	global_load_lds_dwordx4 v[180:181], off
	v_lshl_add_u64 v[180:181], v[234:235], 0, s[28:29]
	s_mov_b32 m0, s68
	s_nop 0
	global_load_lds_dwordx4 v[180:181], off
	s_waitcnt vmcnt(8)
	s_waitcnt lgkmcnt(0)
	s_barrier
	s_waitcnt lgkmcnt(0)
	v_mfma_f32_16x16x32_bf16 v[60:63], v[128:131], v[198:201], v[60:63]
	v_mfma_f32_16x16x32_bf16 v[28:31], v[136:139], v[198:201], v[28:31]
	v_mfma_f32_16x16x32_bf16 v[52:55], v[128:131], v[206:209], v[52:55]
	v_mfma_f32_16x16x32_bf16 v[20:23], v[136:139], v[206:209], v[20:23]
	v_mfma_f32_16x16x32_bf16 v[48:51], v[128:131], v[214:217], v[48:51]
	v_mfma_f32_16x16x32_bf16 v[16:19], v[136:139], v[214:217], v[16:19]
	v_mfma_f32_16x16x32_bf16 v[44:47], v[128:131], v[222:225], v[44:47]
	v_mfma_f32_16x16x32_bf16 v[8:11], v[136:139], v[222:225], v[8:11]
	v_mfma_f32_16x16x32_bf16 v[60:63], v[132:135], v[202:205], v[60:63]
	v_mfma_f32_16x16x32_bf16 v[28:31], v[140:143], v[202:205], v[28:31]
	v_mfma_f32_16x16x32_bf16 v[52:55], v[132:135], v[210:213], v[52:55]
	v_mfma_f32_16x16x32_bf16 v[20:23], v[140:143], v[210:213], v[20:23]
	v_mfma_f32_16x16x32_bf16 v[48:51], v[132:135], v[218:221], v[48:51]
	v_mfma_f32_16x16x32_bf16 v[16:19], v[140:143], v[218:221], v[16:19]
	v_mfma_f32_16x16x32_bf16 v[44:47], v[132:135], v[226:229], v[44:47]
	v_mfma_f32_16x16x32_bf16 v[8:11], v[140:143], v[226:229], v[8:11]
	v_mfma_f32_16x16x32_bf16 v[56:59], v[168:171], v[198:201], v[56:59]
	v_mfma_f32_16x16x32_bf16 v[24:27], v[176:179], v[198:201], v[24:27]
	v_mfma_f32_16x16x32_bf16 v[40:43], v[168:171], v[206:209], v[40:43]
	v_mfma_f32_16x16x32_bf16 v[12:15], v[176:179], v[206:209], v[12:15]
	v_mfma_f32_16x16x32_bf16 v[36:39], v[168:171], v[214:217], v[36:39]
	v_mfma_f32_16x16x32_bf16 v[4:7], v[176:179], v[214:217], v[4:7]
	v_mfma_f32_16x16x32_bf16 v[32:35], v[168:171], v[222:225], v[32:35]
	v_mfma_f32_16x16x32_bf16 v[0:3], v[176:179], v[222:225], v[0:3]
	v_mfma_f32_16x16x32_bf16 v[56:59], v[172:175], v[202:205], v[56:59]
	v_mfma_f32_16x16x32_bf16 v[24:27], v[194:197], v[202:205], v[24:27]
	v_mfma_f32_16x16x32_bf16 v[40:43], v[172:175], v[210:213], v[40:43]
	v_mfma_f32_16x16x32_bf16 v[12:15], v[194:197], v[210:213], v[12:15]
	v_mfma_f32_16x16x32_bf16 v[36:39], v[172:175], v[218:221], v[36:39]
	v_mfma_f32_16x16x32_bf16 v[4:7], v[194:197], v[218:221], v[4:7]
	v_mfma_f32_16x16x32_bf16 v[32:35], v[172:175], v[226:229], v[32:35]
	v_mfma_f32_16x16x32_bf16 v[0:3], v[194:197], v[226:229], v[0:3]
	s_barrier
	s_add_i32 s78, s78, 2
	s_add_u32 s18, s18, 0x100
	s_addc_u32 s19, s19, 0
	s_add_u32 s76, s76, 0x100
	s_addc_u32 s77, s77, 0
	s_cmp_gt_u32 s78, 29
	s_cbranch_scc0 .LBB0_882
	s_and_b64 vcc, exec, s[30:31]
	s_cbranch_vccz .LBB0_885
	s_barrier

; #define PG8_WAIT_V(n) asm volatile("s_waitcnt vmcnt(" #n ")" ::: "memory")
; #define PG8_BAR __builtin_amdgcn_s_barrier()
; template <class Epi, class Sched, bool ALIGN_EPI = false, bool SP2 = false>
; __device__ __forceinline__ void gemm_phase(PG8_LAS unsigned char* lds, const Gemm g, const Sched& S, const Epi& E) {
;     ...
;     PG8_WAIT_V(0);
;     if constexpr (!ALIGN_EPI) { if (wr == 0) PG8_BAR; }
;     PG8_BAR;
.LBB0_916:
	s_setprio 0
	s_waitcnt vmcnt(0)
	s_barrier
